# fgate rows remapped to the XCD's own batch; XCD-local barriers also after phases 9 and 10 (11 of 14 seams local)
# speedup vs baseline: 1.0268x; 1.0046x over previous
.LBB0_193:
	s_and_b64 vcc, exec, s[2:3]
	s_cbranch_vccz .LBB0_300
	s_cmp_gt_i32 s75, 8
	s_mov_b64 s[22:23], -1
	s_cbranch_scc0 .LBB0_300
	s_cmp_gt_i32 s75, 9
	s_mov_b64 s[26:27], -1
	s_cbranch_scc0 .LBB0_299
	v_readlane_b32 s2, v255, 6
	s_add_u32 s6, s0, 0x300000
	s_addc_u32 s7, s1, 0
	v_mov_b32_e32 v1, s2
	ds_read_b64 v[2:3], v1
	s_and_b32 s98, s76, 7
	s_lshl_b32 s98, s98, 5
	s_lshr_b32 s4, s76, 3
	s_add_i32 s98, s98, s4
	s_lshl_b32 s4, s98, 3
	s_add_i32 s4, s4, s71
	s_cmpk_gt_i32 s4, 0x7ff
	v_and_b32_e32 v1, 15, v242
	s_waitcnt lgkmcnt(0)
	v_readfirstlane_b32 s3, v3
	v_readfirstlane_b32 s2, v2
	s_cbranch_scc1 .LBB0_200
	v_and_b32_e32 v8, 48, v243
	v_mov_b32_e32 v9, v0
	v_lshlrev_b32_e32 v4, 11, v1
	v_mov_b32_e32 v5, v0
	v_lshl_add_u64 v[4:5], s[0:1], 0, v[4:5]
	v_lshl_add_u64 v[6:7], s[2:3], 0, v[8:9]
	s_lshl_b32 s2, s98, 7
	s_lshl_b32 s3, s71, 4
	v_lshl_add_u64 v[4:5], v[4:5], 0, v[8:9]
	s_mov_b64 s[10:11], 0x2800000
	s_add_i32 s2, s2, s3
	v_lshl_add_u64 v[2:3], s[80:81], 0, v[8:9]
	v_lshl_add_u64 v[4:5], v[4:5], 0, s[10:11]
	v_lshl_add_u64 v[8:9], s[24:25], 0, v[8:9]
	v_or_b32_e32 v10, s2, v1
	v_readlane_b32 s2, v255, 2
	s_mov_b32 s10, 0x3fb8aa3b

.LBB0_719:
	s_andn2_saveexec_b64 s[2:3], s[2:3]
	s_cbranch_execz .LBB0_144
	v_readlane_b32 s4, v255, 60
	s_lshr_b32 s5, 0x3fd6, s75
	s_and_b32 s5, s5, 1
	s_nop 1
	s_cmp_eq_u32 s4, 0
	s_cselect_b32 s5, s5, 0
	s_cmp_eq_u32 s5, 1
	s_cbranch_scc1 .Lbar_local
	s_mov_b64 s[2:3], exec
	buffer_wbl2 sc1
	s_waitcnt lgkmcnt(0)
	s_waitcnt vmcnt(0)
	v_mbcnt_lo_u32_b32 v1, s2, 0
	v_mbcnt_hi_u32_b32 v1, s3, v1
	v_cmp_eq_u32_e32 vcc, 0, v1
	s_and_saveexec_b64 s[4:5], vcc
	s_cbranch_execz .LBB0_722
	s_bcnt1_i32_b64 s2, s[2:3]
	v_mov_b32_e32 v3, s2
	v_readlane_b32 s2, v254, 56
	v_readlane_b32 s3, v254, 57
	s_nop 4
	global_atomic_add v3, v0, v3, s[2:3] sc0
